# SSM pass 2: all sixteen transposed LDS reads of the C-projection issued up front into distinct registers, MFMAs follow with counted waits
# baseline (speedup 1.0000x reference)
.LBB0_509:
	v_mfma_f32_32x32x16_bf16 v[50:65], v[138:141], v[78:81], 0
	s_add_i32 s76, s76, 1
	v_lshl_add_u64 v[158:159], v[158:159], 0, s[70:71]
	s_cmp_eq_u32 s76, 16
	v_mfma_f32_32x32x16_bf16 v[2:17], v[138:141], v[66:69], 0
	v_mfma_f32_32x32x16_bf16 v[18:33], v[138:141], v[70:73], 0
	v_mfma_f32_32x32x16_bf16 v[34:49], v[138:141], v[74:77], 0
	v_xor_b32_e32 v254, 0x80000000, v156
	v_xor_b32_e32 v255, 0x80000000, v157
	s_nop 9
	v_fmac_f32_e32 v50, v160, v162
	v_fmac_f32_e32 v2, v161, v163
	v_fmac_f32_e32 v18, v160, v164
	v_fmac_f32_e32 v34, v161, v165
	v_fmac_f32_e32 v50, v254, v164
	v_fmac_f32_e32 v2, v255, v165
	v_fmac_f32_e32 v18, v156, v162
	v_fmac_f32_e32 v34, v157, v163
	v_fmac_f32_e32 v51, v160, v50
	v_fmac_f32_e32 v3, v161, v2
	v_fmac_f32_e32 v19, v160, v18
	v_fmac_f32_e32 v35, v161, v34
	v_fmac_f32_e32 v51, v254, v18
	v_fmac_f32_e32 v3, v255, v34
	v_fmac_f32_e32 v19, v156, v50
	v_fmac_f32_e32 v35, v157, v2
	v_fmac_f32_e32 v52, v160, v51
	v_fmac_f32_e32 v4, v161, v3
	v_fmac_f32_e32 v20, v160, v19
	v_fmac_f32_e32 v36, v161, v35
	v_fmac_f32_e32 v52, v254, v19
	v_fmac_f32_e32 v4, v255, v35
	v_fmac_f32_e32 v20, v156, v51
	v_fmac_f32_e32 v36, v157, v3
	v_fmac_f32_e32 v53, v160, v52
	v_fmac_f32_e32 v5, v161, v4
	v_fmac_f32_e32 v21, v160, v20
	v_fmac_f32_e32 v37, v161, v36
	v_fmac_f32_e32 v53, v254, v20
	v_fmac_f32_e32 v5, v255, v36
	v_fmac_f32_e32 v21, v156, v52
	v_fmac_f32_e32 v37, v157, v4
	v_fmac_f32_e32 v54, v160, v53
	v_fmac_f32_e32 v6, v161, v5
	v_fmac_f32_e32 v22, v160, v21
	v_fmac_f32_e32 v38, v161, v37
	v_fmac_f32_e32 v54, v254, v21
	v_fmac_f32_e32 v6, v255, v37
	v_fmac_f32_e32 v22, v156, v53
	v_fmac_f32_e32 v38, v157, v5
	v_fmac_f32_e32 v55, v160, v54
	v_fmac_f32_e32 v7, v161, v6
	v_fmac_f32_e32 v23, v160, v22
	v_fmac_f32_e32 v39, v161, v38
	v_fmac_f32_e32 v55, v254, v22
	v_fmac_f32_e32 v7, v255, v38
	v_fmac_f32_e32 v23, v156, v54
	v_fmac_f32_e32 v39, v157, v6
	v_fmac_f32_e32 v56, v160, v55
	v_fmac_f32_e32 v8, v161, v7
	v_fmac_f32_e32 v24, v160, v23
	v_fmac_f32_e32 v40, v161, v39
	v_fmac_f32_e32 v56, v254, v23
	v_fmac_f32_e32 v8, v255, v39
	v_fmac_f32_e32 v24, v156, v55
	v_fmac_f32_e32 v40, v157, v7
	v_fmac_f32_e32 v57, v160, v56
	v_fmac_f32_e32 v9, v161, v8
	v_fmac_f32_e32 v25, v160, v24
	v_fmac_f32_e32 v41, v161, v40
	v_fmac_f32_e32 v57, v254, v24
	v_fmac_f32_e32 v9, v255, v40
	v_fmac_f32_e32 v25, v156, v56
	v_fmac_f32_e32 v41, v157, v8
	v_fmac_f32_e32 v58, v160, v57
	v_fmac_f32_e32 v10, v161, v9
	v_fmac_f32_e32 v26, v160, v25
	v_fmac_f32_e32 v42, v161, v41
	v_fmac_f32_e32 v58, v254, v25
	v_fmac_f32_e32 v10, v255, v41
	v_fmac_f32_e32 v26, v156, v57
	v_fmac_f32_e32 v42, v157, v9
	v_fmac_f32_e32 v59, v160, v58
	v_fmac_f32_e32 v11, v161, v10
	v_fmac_f32_e32 v27, v160, v26
	v_fmac_f32_e32 v43, v161, v42
	v_fmac_f32_e32 v59, v254, v26
	v_fmac_f32_e32 v11, v255, v42
	v_fmac_f32_e32 v27, v156, v58
	v_fmac_f32_e32 v43, v157, v10
	v_fmac_f32_e32 v60, v160, v59
	v_fmac_f32_e32 v12, v161, v11
	v_fmac_f32_e32 v28, v160, v27
	v_fmac_f32_e32 v44, v161, v43
	v_fmac_f32_e32 v60, v254, v27
	v_fmac_f32_e32 v12, v255, v43
	v_fmac_f32_e32 v28, v156, v59
	v_fmac_f32_e32 v44, v157, v11
	v_fmac_f32_e32 v61, v160, v60
	v_fmac_f32_e32 v13, v161, v12
	v_fmac_f32_e32 v29, v160, v28
	v_fmac_f32_e32 v45, v161, v44
	v_fmac_f32_e32 v61, v254, v28
	v_fmac_f32_e32 v13, v255, v44
	v_fmac_f32_e32 v29, v156, v60
	v_fmac_f32_e32 v45, v157, v12
	v_fmac_f32_e32 v62, v160, v61
	v_fmac_f32_e32 v14, v161, v13
	v_fmac_f32_e32 v30, v160, v29
	v_fmac_f32_e32 v46, v161, v45
	v_fmac_f32_e32 v62, v254, v29
	v_fmac_f32_e32 v14, v255, v45
	v_fmac_f32_e32 v30, v156, v61
	v_fmac_f32_e32 v46, v157, v13
	v_fmac_f32_e32 v63, v160, v62
	v_fmac_f32_e32 v15, v161, v14
	v_fmac_f32_e32 v31, v160, v30
	v_fmac_f32_e32 v47, v161, v46
	v_fmac_f32_e32 v63, v254, v30
	v_fmac_f32_e32 v15, v255, v46
	v_fmac_f32_e32 v31, v156, v62
	v_fmac_f32_e32 v47, v157, v14
	v_fmac_f32_e32 v64, v160, v63
	v_fmac_f32_e32 v16, v161, v15
	v_fmac_f32_e32 v32, v160, v31
	v_fmac_f32_e32 v48, v161, v47
	v_fmac_f32_e32 v64, v254, v31
	v_fmac_f32_e32 v16, v255, v47
	v_fmac_f32_e32 v32, v156, v63
	v_fmac_f32_e32 v48, v157, v15
	v_fmac_f32_e32 v65, v160, v64
	v_fmac_f32_e32 v17, v161, v16
	v_fmac_f32_e32 v33, v160, v32
	v_fmac_f32_e32 v49, v161, v48
	v_fmac_f32_e32 v65, v254, v32
	v_fmac_f32_e32 v17, v255, v48
	v_fmac_f32_e32 v33, v156, v64
	v_fmac_f32_e32 v49, v157, v16
	v_mov_b32_e32 v162, v65
	v_mov_b32_e32 v163, v17
	v_mov_b32_e32 v164, v33
	v_mov_b32_e32 v165, v49
	v_cvt_pk_bf16_f32 v250, v2, v3
	v_cvt_pk_bf16_f32 v251, v4, v5
	ds_write_b64 v185, v[250:251] offset:2304
	v_cvt_pk_bf16_f32 v252, v6, v7
	v_cvt_pk_bf16_f32 v253, v8, v9
	ds_write_b64 v185, v[252:253] offset:2320
	v_cvt_pk_bf16_f32 v250, v10, v11
	v_cvt_pk_bf16_f32 v251, v12, v13
	ds_write_b64 v185, v[250:251] offset:2336
	v_cvt_pk_bf16_f32 v252, v14, v15
	v_cvt_pk_bf16_f32 v253, v16, v17
	ds_write_b64 v185, v[252:253] offset:2352
	v_mfma_f32_32x32x16_bf16 v[2:17], v[94:97], v[138:141], 0
	v_cvt_pk_bf16_f32 v250, v50, v51
	v_cvt_pk_bf16_f32 v251, v52, v53
	ds_write_b64 v185, v[250:251]
	v_cvt_pk_bf16_f32 v252, v54, v55
	v_cvt_pk_bf16_f32 v253, v56, v57
	ds_write_b64 v185, v[252:253] offset:16
	v_cvt_pk_bf16_f32 v250, v58, v59
	v_cvt_pk_bf16_f32 v251, v60, v61
	ds_write_b64 v185, v[250:251] offset:32
	v_cvt_pk_bf16_f32 v252, v62, v63
	v_cvt_pk_bf16_f32 v253, v64, v65
	ds_write_b64 v185, v[252:253] offset:48
	v_mfma_f32_32x32x16_bf16 v[2:17], v[98:101], v[138:141], v[2:17]
	v_cvt_pk_bf16_f32 v250, v18, v19
	v_cvt_pk_bf16_f32 v251, v20, v21
	ds_write_b64 v185, v[250:251] offset:4608
	v_cvt_pk_bf16_f32 v252, v22, v23
	v_cvt_pk_bf16_f32 v253, v24, v25
	ds_write_b64 v185, v[252:253] offset:4624
	v_cvt_pk_bf16_f32 v250, v26, v27
	v_cvt_pk_bf16_f32 v251, v28, v29
	ds_write_b64 v185, v[250:251] offset:4640
	v_cvt_pk_bf16_f32 v252, v30, v31
	v_cvt_pk_bf16_f32 v253, v32, v33
	ds_write_b64 v185, v[252:253] offset:4656
	v_cvt_pk_bf16_f32 v250, v34, v35
	v_cvt_pk_bf16_f32 v251, v36, v37
	ds_write_b64 v185, v[250:251] offset:6912
	v_cvt_pk_bf16_f32 v252, v38, v39
	v_cvt_pk_bf16_f32 v253, v40, v41
	ds_write_b64 v185, v[252:253] offset:6928
	v_cvt_pk_bf16_f32 v250, v42, v43
	v_cvt_pk_bf16_f32 v251, v44, v45
	ds_write_b64 v185, v[250:251] offset:6944
	v_cvt_pk_bf16_f32 v252, v46, v47
	v_cvt_pk_bf16_f32 v253, v48, v49
	ds_write_b64 v185, v[252:253] offset:6960
	s_waitcnt lgkmcnt(0)
	ds_read_b64_tr_b16 v[190:191], v186
	ds_read_b64_tr_b16 v[192:193], v186 offset:288
	ds_read_b64_tr_b16 v[194:195], v186 offset:1152
	ds_read_b64_tr_b16 v[196:197], v186 offset:1440
	ds_read_b64_tr_b16 v[198:199], v186 offset:2304
	ds_read_b64_tr_b16 v[200:201], v186 offset:2592
	ds_read_b64_tr_b16 v[202:203], v186 offset:3456
	ds_read_b64_tr_b16 v[204:205], v186 offset:3744
	ds_read_b64_tr_b16 v[206:207], v186 offset:4608
	ds_read_b64_tr_b16 v[208:209], v186 offset:4896
	ds_read_b64_tr_b16 v[210:211], v186 offset:5760
	ds_read_b64_tr_b16 v[212:213], v186 offset:6048
	ds_read_b64_tr_b16 v[214:215], v186 offset:6912
	ds_read_b64_tr_b16 v[216:217], v186 offset:7200
	ds_read_b64_tr_b16 v[218:219], v186 offset:8064
	ds_read_b64_tr_b16 v[220:221], v186 offset:8352
	v_mov_b64_e32 v[140:141], v[136:137]
	v_mov_b64_e32 v[138:139], v[134:135]
	s_waitcnt lgkmcnt(14)
	v_mfma_f32_32x32x16_bf16 v[2:17], v[102:105], v[190:193], v[2:17]
	s_waitcnt lgkmcnt(12)
	v_mfma_f32_32x32x16_bf16 v[2:17], v[106:109], v[194:197], v[2:17]
	s_waitcnt lgkmcnt(10)
	v_mfma_f32_32x32x16_bf16 v[2:17], v[110:113], v[198:201], v[2:17]
	s_waitcnt lgkmcnt(8)
	v_mfma_f32_32x32x16_bf16 v[2:17], v[114:117], v[202:205], v[2:17]
	s_waitcnt lgkmcnt(6)
	v_mfma_f32_32x32x16_bf16 v[2:17], v[118:121], v[206:209], v[2:17]
	s_waitcnt lgkmcnt(4)
	v_mfma_f32_32x32x16_bf16 v[2:17], v[122:125], v[210:213], v[2:17]
	s_waitcnt lgkmcnt(2)
	v_mfma_f32_32x32x16_bf16 v[2:17], v[126:129], v[214:217], v[2:17]
	s_waitcnt lgkmcnt(0)
	v_mfma_f32_32x32x16_bf16 v[2:17], v[130:133], v[218:221], v[2:17]
	s_nop 11
	v_mul_f32_e32 v11, 0x3d372713, v3
	v_mul_f32_e32 v12, 0x3d372713, v4
	v_mul_f32_e32 v11, v3, v11
	v_mul_f32_e32 v12, v4, v12
	v_fma_f32 v11, v3, v11, v3
	v_fma_f32 v12, v4, v12, v4
	v_mul_f32_e32 v11, 0x3fcc422a, v11
	v_mul_f32_e32 v12, 0x3fcc422a, v12
	v_mul_f32_e32 v10, 0x3d372713, v2
	v_mul_f32_e32 v11, 0xbfb8aa3b, v11
	v_mul_f32_e32 v12, 0xbfb8aa3b, v12
	v_mul_f32_e32 v10, v2, v10
	v_exp_f32_e32 v11, v11
	v_exp_f32_e32 v12, v12
	v_fma_f32 v10, v2, v10, v2
	v_mul_f32_e32 v10, 0x3fcc422a, v10
	v_mul_f32_e32 v10, 0xbfb8aa3b, v10
	v_exp_f32_e32 v10, v10
	v_add_f32_e32 v11, 1.0, v11
	v_add_f32_e32 v12, 1.0, v12
	v_mul_f32_e32 v13, 0x3d372713, v5
	v_rcp_f32_e32 v11, v11
	v_rcp_f32_e32 v12, v12
	v_mul_f32_e32 v13, v5, v13
	v_fma_f32 v13, v5, v13, v5
	v_mul_f32_e32 v13, 0x3fcc422a, v13
	v_add_f32_e32 v10, 1.0, v10
	v_mul_f32_e32 v13, 0xbfb8aa3b, v13
	v_rcp_f32_e32 v10, v10
	v_exp_f32_e32 v13, v13
	v_mul_f32_e32 v3, v3, v11
	v_mul_f32_e32 v4, v4, v12
	v_mul_f32_e32 v11, 0x3d372713, v6
	v_mul_f32_e32 v12, 0x3d372713, v7
	v_mul_f32_e32 v11, v6, v11
	v_mul_f32_e32 v12, v7, v12
	v_fma_f32 v11, v6, v11, v6
	v_fma_f32 v12, v7, v12, v7
	v_mul_f32_e32 v11, 0x3fcc422a, v11
	v_mul_f32_e32 v12, 0x3fcc422a, v12
	v_mul_f32_e32 v2, v2, v10
	v_add_f32_e32 v10, 1.0, v13
	v_mul_f32_e32 v11, 0xbfb8aa3b, v11
	v_mul_f32_e32 v12, 0xbfb8aa3b, v12
	v_rcp_f32_e32 v10, v10
	v_exp_f32_e32 v11, v11
	v_exp_f32_e32 v12, v12
	v_mul_f32_e32 v13, 0x3d372713, v9
	v_mul_f32_e32 v5, v5, v10
	v_add_f32_e32 v10, 1.0, v11
	v_add_f32_e32 v11, 1.0, v12
	v_mul_f32_e32 v12, 0x3d372713, v8
	v_mul_f32_e32 v12, v8, v12
	v_mul_f32_e32 v13, v9, v13
	v_fma_f32 v12, v8, v12, v8
	v_fma_f32 v13, v9, v13, v9
	v_mul_f32_e32 v12, 0x3fcc422a, v12
	v_mul_f32_e32 v13, 0x3fcc422a, v13
	v_mul_f32_e32 v12, 0xbfb8aa3b, v12
	v_mul_f32_e32 v13, 0xbfb8aa3b, v13
	v_exp_f32_e32 v12, v12
	v_exp_f32_e32 v13, v13
	v_rcp_f32_e32 v10, v10
	v_rcp_f32_e32 v11, v11
	v_add_f32_e32 v12, 1.0, v12
	v_add_f32_e32 v13, 1.0, v13
	v_rcp_f32_e32 v12, v12
	v_rcp_f32_e32 v13, v13
	v_cvt_pk_bf16_f32 v2, v2, v3
	v_cvt_pk_bf16_f32 v3, v4, v5
	v_mul_f32_e32 v6, v6, v10
	v_mul_f32_e32 v7, v7, v11
	v_mul_f32_e32 v8, v8, v12
	v_mul_f32_e32 v9, v9, v13
	v_cvt_pk_bf16_f32 v4, v6, v7
	v_cvt_pk_bf16_f32 v5, v8, v9
	global_store_dwordx2 v[168:169], v[2:3], off
	global_store_dwordx2 v[168:169], v[4:5], off offset:16
	v_lshl_add_u64 v[168:169], v[168:169], 0, s[70:71]
	s_cbranch_scc1 .LBB0_493
	s_waitcnt vmcnt(2)
	v_mov_b64_e32 v[136:137], v[84:85]
	v_mov_b64_e32 v[134:135], v[82:83]
	v_mov_b64_e32 v[82:83], v[90:91]
	v_mov_b64_e32 v[84:85], v[92:93]
	v_mov_b64_e32 v[92:93], v[88:89]
	s_cmp_gt_u32 s76, 11
	v_mov_b64_e32 v[90:91], v[86:87]
	s_cbranch_scc1 .LBB0_509
	s_branch .Lssm2_load
